# diff attention: P fed to PV MFMAs straight from the accumulator layout (8 v_permlane32_swap per step removed) by keeping the V tile in LDS in matching key order
# speedup vs baseline: 1.0155x; 1.0017x over previous
; __device__ __forceinline__ int v_st(int k, int c) { const int kk = (k & ~0xC) | ((k & 4) << 1) | ((k & 8) >> 1); return ((kk >> 3) * 4 + (c >> 5)) * 512 + ((kk & 7) * 32 + (c & 31)) * 2; }
; __device__ __forceinline__ int v_rd_base(int lane) { return ((lane & 3) << 3) | (((lane >> 2) & 3) << 6) | (((lane >> 4) & 1) << 5) | (((lane >> 5) & 1) << 8); }
; #define SLOAD(i, k0) do { sr_[i].vs0 = ld8(&Vg[(long)((k0) + sr) * LDP + sc]); sr_[i].vs1 = ld8(&Vg[(long)((k0) + 32 + sr) * LDP + sc]); \
;     sr_[i].ks0 = ld8(&Kg[(long)((k0) + sr) * LDP + sc]); sr_[i].ks1 = ld8(&Kg[(long)((k0) + 32 + sr) * LDP + sc]); } while (0)
; #define SWRITE(off, i) do { *(bf16x8*)(V_lds + (off) + vst0) = sr_[i].vs0;          \
;     *(bf16x8*)(V_lds + (off) + vst1) = sr_[i].vs1; int kc = sc * 2;               \
;     *(bf16x8*)(K_lds + (off) + KSWZ(sr, kc)) = sr_[i].ks0;                       \
;     *(bf16x8*)(K_lds + (off) + KSWZ(32 + sr, kc)) = sr_[i].ks1; } while (0)
; template <int MODE, int ORD> ...
;     ...
;   const bf16* Qw = Qb + (long)(wq * 32 + r32) * LDP + cst * 64 + hi * 8;
; #pragma unroll
;   for (int d0 = 0; d0 < ND0; ++d0) qr[d0] = scale_bf16x8(ld8(Qw + d0 * 16), C);
;   const int qpos = qpos0 + wq * 32 + r32;
;   const int qw0 = qpos0 + wq * 32;
;   const int cboff = cst * 128;
;   int sr = tid >> 4, sc = (tid & 15) * 8, vst0 = v_st(sr, sc), vst1 = v_st(32 + sr, sc);
;   int vb0 = (int)(uintptr_t)V_lds + v_rd_base(lane);
;   const bf16* Kg = Kh + (long)kbeg * LDP; const bf16* Vg = Vh + (long)kbeg * LDP;
;   struct { bf16x8 vs0, vs1, ks0, ks1; } sr_[1];
;     ...
;   SLOAD(SE, 0); asm volatile("s_waitcnt vmcnt(0)" ::: "memory"); SWRITE(0, SE); __syncthreads();
.LBB0_157:
	s_or_b64 exec, exec, s[0:1]
	s_lshl_b32 s68, s6, 7
	s_add_u32 s6, s10, s68
	s_addc_u32 s7, s11, 0
	s_mul_i32 s0, s7, 0x2400
	s_mul_hi_u32 s1, s6, 0x2400
	s_add_i32 s1, s1, s0
	s_mul_i32 s0, s6, 0x2400
	s_add_u32 s0, s20, s0
	s_addc_u32 s1, s21, s1
	s_lshl_b32 s78, s80, 8
	s_add_u32 s0, s0, s78
	s_mul_i32 s18, s11, 0x2400
	s_mul_hi_u32 s19, s10, 0x2400
	s_addc_u32 s1, s1, 0
	s_add_i32 s19, s19, s18
	s_mul_i32 s18, s10, 0x2400
	s_add_u32 s18, s20, s18
	s_addc_u32 s19, s21, s19
	s_add_u32 s18, s18, s78
	s_addc_u32 s19, s19, 0
	s_add_u32 s42, s18, 0x1000
	s_addc_u32 s43, s19, 0
	s_and_b32 s66, s62, 3
	v_and_b32_e32 v184, 31, v40
	s_lshl_b32 s79, s66, 5
	v_or_b32_e32 v0, s79, v184
	v_mul_u32_u24_e32 v0, 0x1200, v0
	s_ashr_i32 s64, s63, 8
	v_lshlrev_b32_e32 v204, 1, v0
	v_lshl_add_u64 v[0:1], s[0:1], 0, v[204:205]
	s_lshl_b32 s0, s64, 6
	v_bfe_u32 v185, v40, 5, 1
	s_ashr_i32 s1, s0, 31
	v_lshl_add_u64 v[0:1], s[0:1], 1, v[0:1]
	v_lshlrev_b32_e32 v204, 4, v185
	v_lshl_add_u64 v[4:5], v[0:1], 0, v[204:205]
	global_load_dwordx4 v[0:3], v[4:5], off
	v_ashrrev_i32_e32 v38, 4, v40
	v_lshlrev_b32_e32 v16, 3, v40
	v_add_u32_e32 v17, 32, v38
	v_and_b32_e32 v41, 0x78, v16
	v_lshlrev_b32_e32 v19, 4, v40
	v_and_b32_e32 v20, 0xfffff0, v38
	v_lshlrev_b32_e32 v21, 1, v38
	v_lshrrev_b32_e32 v22, 1, v38
	v_and_b32_e32 v23, 3, v38
	v_and_b32_e32 v47, 0xf0, v19
	v_and_or_b32 v19, v21, 8, v20
	v_and_or_b32 v20, v22, 4, v23
	v_and_b32_e32 v22, 0xfffff0, v17
	v_lshlrev_b32_e32 v23, 1, v17
	v_and_b32_e32 v18, 0xf0, v40
	v_bfe_u32 v16, v16, 5, 2
	v_lshlrev_b32_e32 v24, 8, v38
	v_lshlrev_b32_e32 v21, 1, v41
	v_lshrrev_b32_e32 v19, 1, v19
	v_and_or_b32 v22, v23, 8, v22
	v_bitop3_b32 v191, v21, v24, v18 bitop3:0xde
	v_lshlrev_b32_e32 v20, 6, v20
	v_and_b32_e32 v23, 48, v21
	v_lshlrev_b32_e32 v39, 8, v184
	s_add_i32 s69, 0, 0x18800
	v_lshl_or_b32 v48, s64, 7, v204
	v_xad_u32 v188, v48, v47, v39
	v_add_u32_e32 v42, 0, v191
	s_or_b32 s92, s79, s68
	s_cmpk_lt_u32 s92, 0xbf
	s_cselect_b64 s[48:49], -1, 0
	v_readlane_b32 s34, v255, 35
	s_mov_b64 s[56:57], -1
	s_and_b64 vcc, exec, s[48:49]
	v_lshlrev_b32_e32 v197, 2, v185
	s_waitcnt vmcnt(0)
	v_lshlrev_b32_e32 v6, 16, v0
	v_and_b32_e32 v0, 0xffff0000, v0
	v_lshlrev_b32_e32 v7, 16, v1
	v_and_b32_e32 v1, 0xffff0000, v1
	v_lshlrev_b32_e32 v8, 16, v2
	v_and_b32_e32 v2, 0xffff0000, v2
	v_lshlrev_b32_e32 v9, 16, v3
	v_and_b32_e32 v3, 0xffff0000, v3
	v_mul_f32_e32 v0, 0x3e38aa3b, v0
	v_mul_f32_e32 v1, 0x3e38aa3b, v1
	v_mul_f32_e32 v2, 0x3e38aa3b, v2
	v_mul_f32_e32 v3, 0x3e38aa3b, v3
	v_mul_f32_e32 v6, 0x3e38aa3b, v6
	v_mul_f32_e32 v7, 0x3e38aa3b, v7
	v_mul_f32_e32 v8, 0x3e38aa3b, v8
	v_mul_f32_e32 v9, 0x3e38aa3b, v9
	v_cvt_pk_bf16_f32 v128, v6, v0
	v_cvt_pk_bf16_f32 v129, v7, v1
	v_cvt_pk_bf16_f32 v130, v8, v2
	v_cvt_pk_bf16_f32 v131, v9, v3
	global_load_dwordx4 v[0:3], v[4:5], off offset:32
	s_waitcnt vmcnt(0)
	v_lshlrev_b32_e32 v6, 16, v0
	v_and_b32_e32 v0, 0xffff0000, v0
	v_lshlrev_b32_e32 v7, 16, v1
	v_and_b32_e32 v1, 0xffff0000, v1
	v_lshlrev_b32_e32 v8, 16, v2
	v_and_b32_e32 v2, 0xffff0000, v2
	v_lshlrev_b32_e32 v9, 16, v3
	v_and_b32_e32 v3, 0xffff0000, v3
	v_mul_f32_e32 v0, 0x3e38aa3b, v0
	v_mul_f32_e32 v1, 0x3e38aa3b, v1
	v_mul_f32_e32 v2, 0x3e38aa3b, v2
	v_mul_f32_e32 v3, 0x3e38aa3b, v3
	v_mul_f32_e32 v6, 0x3e38aa3b, v6
	v_mul_f32_e32 v7, 0x3e38aa3b, v7
	v_mul_f32_e32 v8, 0x3e38aa3b, v8
	v_mul_f32_e32 v9, 0x3e38aa3b, v9
	v_cvt_pk_bf16_f32 v132, v6, v0
	v_cvt_pk_bf16_f32 v133, v7, v1
	v_cvt_pk_bf16_f32 v134, v8, v2
	v_cvt_pk_bf16_f32 v135, v9, v3
	global_load_dwordx4 v[0:3], v[4:5], off offset:64
	s_waitcnt vmcnt(0)
	v_lshlrev_b32_e32 v6, 16, v0
	v_and_b32_e32 v0, 0xffff0000, v0
	v_lshlrev_b32_e32 v7, 16, v1
	v_and_b32_e32 v1, 0xffff0000, v1
	v_lshlrev_b32_e32 v8, 16, v2
	v_and_b32_e32 v2, 0xffff0000, v2
	v_lshlrev_b32_e32 v9, 16, v3
	v_and_b32_e32 v3, 0xffff0000, v3
	v_mul_f32_e32 v0, 0x3e38aa3b, v0
	v_mul_f32_e32 v1, 0x3e38aa3b, v1
	v_mul_f32_e32 v2, 0x3e38aa3b, v2
	v_mul_f32_e32 v3, 0x3e38aa3b, v3
	v_mul_f32_e32 v6, 0x3e38aa3b, v6
	v_mul_f32_e32 v7, 0x3e38aa3b, v7
	v_mul_f32_e32 v8, 0x3e38aa3b, v8
	v_mul_f32_e32 v9, 0x3e38aa3b, v9
	v_cvt_pk_bf16_f32 v136, v6, v0
	v_cvt_pk_bf16_f32 v137, v7, v1
	v_cvt_pk_bf16_f32 v138, v8, v2
	v_cvt_pk_bf16_f32 v139, v9, v3
	global_load_dwordx4 v[0:3], v[4:5], off offset:96
	v_mad_i64_i32 v[4:5], s[0:1], v38, s73, 0
	v_mad_i64_i32 v[6:7], s[0:1], v17, s73, 0
	v_or_b32_e32 v4, v4, v41
	v_or_b32_e32 v6, v6, v41
	v_lshlrev_b64 v[4:5], 1, v[4:5]
	v_lshlrev_b64 v[6:7], 1, v[6:7]
	v_lshl_add_u64 v[8:9], s[18:19], 0, v[4:5]
	v_lshl_add_u64 v[12:13], s[18:19], 0, v[6:7]
	v_lshl_add_u64 v[4:5], s[42:43], 0, v[4:5]
	v_lshl_add_u64 v[6:7], s[42:43], 0, v[6:7]
	v_lshlrev_b32_e32 v17, 8, v17
	v_bitop3_b32 v192, v21, v17, v18 bitop3:0xde
	v_or_b32_e32 v17, v19, v16
	v_lshrrev_b32_e32 v18, 1, v22
	v_lshlrev_b32_e32 v17, 9, v17
	v_or_b32_e32 v16, v18, v16
	v_lshlrev_b32_e32 v16, 9, v16
	v_or3_b32 v193, v17, v20, v23
	v_or3_b32 v194, v16, v20, v23
	v_bfe_u32 v193, v40, 2, 2
	v_lshrrev_b32_e32 v194, 7, v40
	v_lshl_add_u32 v193, v194, 2, v193
	v_lshlrev_b32_e32 v193, 9, v193
	v_bfe_u32 v194, v40, 4, 3
	v_lshl_or_b32 v193, v194, 6, v193
	v_or_b32_e32 v193, v193, v23
	v_add_u32_e32 v194, 0x2000, v193
	v_add_u32_e32 v44, 0, v193
	v_mov_b32_e32 v16, s69
	v_add_u32_e32 v43, 0, v192
	v_add_u32_e32 v45, 0, v194
	s_waitcnt vmcnt(0)
	v_lshlrev_b32_e32 v10, 16, v0
	v_and_b32_e32 v0, 0xffff0000, v0
	v_lshlrev_b32_e32 v11, 16, v1
	v_and_b32_e32 v1, 0xffff0000, v1
	v_lshlrev_b32_e32 v14, 16, v2
	v_and_b32_e32 v2, 0xffff0000, v2
	v_lshlrev_b32_e32 v15, 16, v3
	v_and_b32_e32 v3, 0xffff0000, v3
	v_mul_f32_e32 v10, 0x3e38aa3b, v10
	v_mul_f32_e32 v0, 0x3e38aa3b, v0
	v_mul_f32_e32 v11, 0x3e38aa3b, v11
	v_mul_f32_e32 v1, 0x3e38aa3b, v1
	v_mul_f32_e32 v14, 0x3e38aa3b, v14
	v_mul_f32_e32 v2, 0x3e38aa3b, v2
	v_mul_f32_e32 v15, 0x3e38aa3b, v15
	v_mul_f32_e32 v3, 0x3e38aa3b, v3
	v_cvt_pk_bf16_f32 v140, v10, v0
	v_cvt_pk_bf16_f32 v141, v11, v1
	v_cvt_pk_bf16_f32 v142, v14, v2
	v_cvt_pk_bf16_f32 v143, v15, v3
	global_load_dwordx4 v[0:3], v[4:5], off
	s_nop 0
	global_load_dwordx4 v[4:7], v[6:7], off
	s_nop 0
	global_load_dwordx4 v[8:11], v[8:9], off offset:2048
	s_nop 0
	global_load_dwordx4 v[12:15], v[12:13], off offset:2048
	s_waitcnt vmcnt(0)
	s_waitcnt vmcnt(3)
	ds_write_b128 v44, v[0:3]
	s_waitcnt vmcnt(2)
	ds_write_b128 v45, v[4:7]
	s_waitcnt vmcnt(1)
	ds_write_b128 v42, v[8:11] offset:16384
	s_waitcnt vmcnt(0)
	ds_write_b128 v43, v[12:15] offset:16384
	s_waitcnt lgkmcnt(0)
	s_barrier
; #define SETBE(t) do { TCLS(t); const float bt_ = near_ ? 0.f : ((rmax_ <= -128) ? bL : bR); \
;     if (bt_ != be_cur) { const float d_ = bt_ - be_cur; _Pragma("unroll") for (int r = 0; r < 16; ++r) negm[r] += d_; be_cur = bt_; } } while (0)
; template <int ND0> __device__ __forceinline__ void qkt(f32x16& p0, f32x16& p1, const char* Ks, const bf16x8* qr, int r32, int hi, int cboff, const f32x16& ci) {
; #pragma unroll
;   for (int d0 = 0; d0 < ND0; ++d0) { int cb = cboff + (d0 * 16 + hi * 8) * 2;
;     bf16x8 b0 = *reinterpret_cast<const bf16x8*>(Ks + KSWZ(r32, cb));
;     bf16x8 b1 = *reinterpret_cast<const bf16x8*>(Ks + KSWZ(32 + r32, cb));
;     if (d0 == 0) { p0 = __builtin_amdgcn_mfma_f32_32x32x16_bf16(b0, qr[0], ci, 0, 0, 0); p1 = __builtin_amdgcn_mfma_f32_32x32x16_bf16(b1, qr[0], ci, 0, 0, 0); }
;     else { p0 = __builtin_amdgcn_mfma_f32_32x32x16_bf16(b0, qr[d0], p0, 0, 0, 0); p1 = __builtin_amdgcn_mfma_f32_32x32x16_bf16(b1, qr[d0], p1, 0, 0, 0); } }
; }
; template <int MODE, int ORD> ...
;     ...
;   bL = tab[0]; bR = tab[256];
;   SETBE(0); qkt<ND0>(pA0, pA1, K_lds, qr, r32, hi, cboff, negm); BIAS(pA0, pA1, 0); partialSM2<MODE == 0>(pA0, pA1, m_reg, negm, alA);
	ds_read_b32 v195, v16
	v_add_u32_e32 v16, 0, v188
	ds_read_b128 v[34:37], v16 offset:16384
	v_bfrev_b32_e32 v0, 1
	s_waitcnt lgkmcnt(1)
	v_cndmask_b32_e64 v46, v195, 0, s[48:49]
	v_cmp_neq_f32_e64 s[0:1], 0, v46
	s_nop 1
	v_cndmask_b32_e64 v0, v0, v46, s[0:1]
	v_mov_b32_e32 v1, v0
	v_mov_b32_e32 v2, v0
	v_mov_b32_e32 v3, v0
	v_mov_b32_e32 v4, v0
	v_mov_b32_e32 v5, v0
	v_mov_b32_e32 v6, v0
	v_mov_b32_e32 v7, v0
	v_mov_b32_e32 v8, v0
	v_mov_b32_e32 v9, v0
	v_mov_b32_e32 v10, v0
	v_mov_b32_e32 v11, v0
	v_mov_b32_e32 v12, v0
	v_mov_b32_e32 v13, v0
	v_mov_b32_e32 v14, v0
	v_mov_b32_e32 v15, v0
	s_waitcnt lgkmcnt(0)
	s_nop 0
	v_mfma_f32_32x32x16_bf16 v[18:33], v[34:37], v[128:131], v[0:15]
	ds_read_b128 v[34:37], v16 offset:24576
	v_or_b32_e32 v16, 32, v48
	v_xad_u32 v196, v16, v47, v39
	v_mov_b64_e32 v[16:17], v[14:15]
	v_add_u32_e32 v49, 0, v196
	s_nop 1
	v_mov_b64_e32 v[14:15], v[12:13]
	v_mov_b64_e32 v[12:13], v[10:11]
	v_mov_b64_e32 v[10:11], v[8:9]
	v_mov_b64_e32 v[8:9], v[6:7]
	v_mov_b64_e32 v[6:7], v[4:5]
	v_mov_b64_e32 v[4:5], v[2:3]
	v_mov_b64_e32 v[2:3], v[0:1]
	v_or_b32_e32 v1, 64, v48
	v_xad_u32 v190, v1, v47, v39
	s_waitcnt lgkmcnt(0)
	v_mfma_f32_32x32x16_bf16 v[2:17], v[34:37], v[128:131], v[2:17]
	ds_read_b128 v[34:37], v49 offset:16384
	v_add_u32_e32 v1, 0, v190
	s_waitcnt lgkmcnt(0)
	v_mfma_f32_32x32x16_bf16 v[18:33], v[34:37], v[132:135], v[18:33]
	ds_read_b128 v[34:37], v49 offset:24576
	s_waitcnt lgkmcnt(0)
	v_mfma_f32_32x32x16_bf16 v[2:17], v[34:37], v[132:135], v[2:17]
	ds_read_b128 v[34:37], v1 offset:16384
	s_waitcnt lgkmcnt(0)
	v_mfma_f32_32x32x16_bf16 v[18:33], v[34:37], v[136:139], v[18:33]
	ds_read_b128 v[34:37], v1 offset:24576
	v_or_b32_e32 v1, 0x60, v48
	v_xad_u32 v189, v1, v47, v39
	v_add_u32_e32 v1, 0, v189
	s_waitcnt lgkmcnt(0)
	v_mfma_f32_32x32x16_bf16 v[2:17], v[34:37], v[136:139], v[2:17]
	ds_read_b128 v[34:37], v1 offset:16384
	s_waitcnt lgkmcnt(0)
	v_mfma_f32_32x32x16_bf16 v[18:33], v[34:37], v[140:143], v[18:33]
	ds_read_b128 v[34:37], v1 offset:24576
	v_mov_b32_e32 v1, s34
	ds_read_b32 v200, v1
	s_waitcnt lgkmcnt(1)
	v_mfma_f32_32x32x16_bf16 v[2:17], v[34:37], v[140:143], v[2:17]
	s_cbranch_vccnz .LBB0_159
	v_lshlrev_b32_e32 v1, 2, v185
	s_mov_b64 s[56:57], 0

; __device__ __forceinline__ float max3f(float a, float b, float c) { float r; asm("v_max3_f32 %0, %1, %2, %3" : "=v"(r) : "v"(a), "v"(b), "v"(c)); return r; }
; #define SLOAD(i, k0) do { sr_[i].vs0 = ld8(&Vg[(long)((k0) + sr) * LDP + sc]); sr_[i].vs1 = ld8(&Vg[(long)((k0) + 32 + sr) * LDP + sc]); \
;     sr_[i].ks0 = ld8(&Kg[(long)((k0) + sr) * LDP + sc]); sr_[i].ks1 = ld8(&Kg[(long)((k0) + 32 + sr) * LDP + sc]); } while (0)
; #define SWRITE(off, i) do { *(bf16x8*)(V_lds + (off) + vst0) = sr_[i].vs0;          \
;     *(bf16x8*)(V_lds + (off) + vst1) = sr_[i].vs1; int kc = sc * 2;               \
;     *(bf16x8*)(K_lds + (off) + KSWZ(sr, kc)) = sr_[i].ks0;                       \
;     *(bf16x8*)(K_lds + (off) + KSWZ(32 + sr, kc)) = sr_[i].ks1; } while (0)
; #define SWAIT() asm volatile("s_waitcnt vmcnt(0)" ::: "memory")
; template <bool FIRST> __device__ __forceinline__ void partialSM2(f32x16& p0, f32x16& p1, float& m_ref, f32x16& negm, float& alpha) {
;   float pmax = max3f(p0[0], p0[1], p1[0]), pmb = max3f(p0[2], p0[3], p1[1]);
;   pmax = max3f(pmax, p1[2], p1[3]);
; #pragma unroll
;   for (int r = 4; r < 16; r += 4) { pmax = max3f(pmax, p0[r], p0[r + 1]); pmb = max3f(pmb, p0[r + 2], p0[r + 3]); pmax = max3f(pmax, p1[r], p1[r + 1]); pmb = max3f(pmb, p1[r + 2], p1[r + 3]); }
;   pmax = max3f(pmax, pmb, pmb);
;   { auto rr = __builtin_amdgcn_permlane32_swap(__float_as_uint(pmax), __float_as_uint(pmax), false, false);
;     pmax = fmaxf(__uint_as_float(rr[0]), __uint_as_float(rr[1])); }
;   alpha = 1.f;
;   if (FIRST || !__builtin_expect(__all(pmax <= THR), 1)) {
;     const float dl = FIRST ? pmax : fmaxf(pmax, 0.f); m_ref += dl; if (!FIRST) alpha = __builtin_amdgcn_exp2f(-dl);
; #pragma unroll
;     for (int r = 0; r < 16; ++r) { p0[r] -= dl; p1[r] -= dl; negm[r] -= dl; }
;   }
; #pragma unroll
;   for (int r = 0; r < 16; ++r) p0[r] = __builtin_amdgcn_exp2f(p0[r]);
; template <int MODE, int ORD> ...
;     ...
;   SETBE(0); qkt<ND0>(pA0, pA1, K_lds, qr, r32, hi, cboff, negm); BIAS(pA0, pA1, 0); partialSM2<MODE == 0>(pA0, pA1, m_reg, negm, alA);
;   SLOAD(SO, KVBLK);
;   SWAIT(); SWRITE(SLOT, SO); __syncthreads();
;   int op = 0, oc = SLOT, on = 2 * SLOT;
.LBB0_162:
	v_and_b32_e32 v1, 63, v40
	v_lshlrev_b32_e32 v35, 4, v1
	v_lshlrev_b32_e32 v34, 3, v1
	v_and_b32_e32 v35, 0xc0, v35
	v_lshlrev_b32_e32 v36, 1, v1
	v_and_or_b32 v35, v34, 24, v35
	v_and_b32_e32 v36, 32, v36
	v_and_b32_e32 v34, 0x100, v34
	s_cmp_lg_u32 0, -1
	v_or3_b32 v34, v35, v36, v34
	s_cselect_b32 s34, 0, 0
	v_add_u32_e32 v199, s34, v34
	v_max3_f32 v34, v18, v19, v2
	v_max3_f32 v35, v20, v21, v3
	v_cndmask_b32_e64 v214, 0, v46, s[0:1]
	v_max3_f32 v34, v34, v4, v5
	v_max3_f32 v35, v35, v24, v25
	s_and_b32 s0, s63, 0x3fffffc0
	v_max3_f32 v34, v34, v22, v23
	v_max3_f32 v35, v35, v8, v9
	s_lshl_b32 s0, s0, 2
	v_max3_f32 v34, v34, v6, v7
	v_max3_f32 v35, v35, v28, v29
	v_add_u32_e32 v36, 0x60, v38
	v_max3_f32 v34, v34, v26, v27
	s_add_i32 s49, s0, 0
	v_max3_f32 v58, v34, v10, v11
	v_add_u32_e32 v34, 64, v38
	v_max3_f32 v59, v35, v12, v13
	v_mad_i64_i32 v[34:35], s[0:1], v34, s73, 0
	v_mad_i64_i32 v[36:37], s[0:1], v36, s73, 0
	v_or_b32_e32 v34, v34, v41
	v_or_b32_e32 v36, v36, v41
	v_lshlrev_b64 v[50:51], 1, v[34:35]
	v_lshlrev_b64 v[52:53], 1, v[36:37]
	v_lshl_add_u64 v[34:35], s[42:43], 0, v[50:51]
	v_lshl_add_u64 v[46:47], s[42:43], 0, v[52:53]
	v_lshl_add_u64 v[50:51], s[18:19], 0, v[50:51]
	v_lshl_add_u64 v[54:55], s[18:19], 0, v[52:53]
	global_load_dwordx4 v[34:37], v[34:35], off
	s_nop 0
	global_load_dwordx4 v[46:49], v[46:47], off
	s_nop 0
	global_load_dwordx4 v[50:53], v[50:51], off offset:2048
	s_nop 0
	global_load_dwordx4 v[54:57], v[54:55], off offset:2048
	v_max3_f32 v41, v58, v30, v31
	v_max3_f32 v58, v59, v32, v33
	s_add_i32 s68, s68, s79
	v_max3_f32 v41, v41, v14, v15
	v_max3_f32 v58, v58, v16, v17
	v_ashrrev_i32_e32 v39, 31, v38
	v_max3_f32 v41, v41, v58, v58
	v_cmp_gt_u32_e64 s[0:1], 32, v1
	v_mov_b32_e32 v58, v41
	s_nop 1
	v_permlane32_swap_b32_e32 v41, v58
	v_max_f32_e32 v58, v58, v58
	v_max_f32_e32 v41, v41, v41
	v_max_f32_e32 v41, v41, v58
	v_sub_f32_e32 v64, v0, v41
	v_add_u32_e32 v0, s68, v184
	v_sub_f32_e32 v81, v3, v41
	v_sub_f32_e32 v80, v2, v41
	v_sub_u32_e32 v202, v197, v0
	v_lshl_add_u64 v[0:1], s[10:11], 0, v[38:39]
	v_mov_b32_e32 v2, s78
	v_mov_b32_e32 v3, v205
	v_mad_u64_u32 v[2:3], s[10:11], v0, s53, v[2:3]
	v_mov_b32_e32 v0, v3
	v_sub_f32_e32 v18, v18, v41
	v_sub_f32_e32 v19, v19, v41
	v_sub_f32_e32 v20, v20, v41
	v_sub_f32_e32 v21, v21, v41
	v_sub_f32_e32 v22, v22, v41
	v_sub_f32_e32 v23, v23, v41
	v_sub_f32_e32 v24, v24, v41
	v_sub_f32_e32 v25, v25, v41
	v_sub_f32_e32 v26, v26, v41
	v_sub_f32_e32 v27, v27, v41
	v_sub_f32_e32 v28, v28, v41
	v_sub_f32_e32 v29, v29, v41
	v_sub_f32_e32 v30, v30, v41
	v_sub_f32_e32 v31, v31, v41
	v_sub_f32_e32 v32, v32, v41
	v_sub_f32_e32 v33, v33, v41
	v_mad_u64_u32 v[0:1], s[10:11], v1, s53, v[0:1]
	v_exp_f32_e32 v173, v18
	v_exp_f32_e32 v175, v19
	v_exp_f32_e32 v171, v20
	v_exp_f32_e32 v174, v21
	v_exp_f32_e32 v169, v22
	v_exp_f32_e32 v172, v23
	v_exp_f32_e32 v168, v24
	v_exp_f32_e32 v170, v25
	v_exp_f32_e32 v165, v26
	v_exp_f32_e32 v167, v27
	v_exp_f32_e32 v163, v28
	v_exp_f32_e32 v166, v29
	v_exp_f32_e32 v161, v30
	v_exp_f32_e32 v164, v31
	v_exp_f32_e32 v160, v32
	v_exp_f32_e32 v162, v33
	v_and_b32_e32 v1, 15, v40
	v_readlane_b32 s10, v255, 31
	v_sub_f32_e32 v93, v15, v41
	v_sub_f32_e32 v92, v14, v41
	s_waitcnt vmcnt(0)
	v_lshl_or_b32 v2, v1, 4, v2
	v_mov_b32_e32 v3, v0
	v_readlane_b32 s11, v255, 32
	v_mov_b32_e32 v14, v205
	v_mov_b32_e32 v15, v205
	s_add_i32 s49, s49, 0x18000
	v_sub_f32_e32 v95, v17, v41
	v_sub_f32_e32 v94, v16, v41
	v_sub_f32_e32 v91, v13, v41
	v_sub_f32_e32 v90, v12, v41
	v_sub_f32_e32 v89, v11, v41
	v_sub_f32_e32 v88, v10, v41
	v_sub_f32_e32 v87, v9, v41
	v_sub_f32_e32 v86, v8, v41
	v_sub_f32_e32 v85, v7, v41
	v_sub_f32_e32 v84, v6, v41
	v_sub_f32_e32 v83, v5, v41
	v_sub_f32_e32 v82, v4, v41
	s_waitcnt vmcnt(3)
	ds_write_b128 v44, v[34:37] offset:32768
	s_waitcnt vmcnt(2)
	ds_write_b128 v45, v[46:49] offset:32768
	s_waitcnt vmcnt(1)
	ds_write_b128 v42, v[50:53] offset:49152
	s_waitcnt vmcnt(0)
	ds_write_b128 v43, v[54:57] offset:49152
	v_lshl_add_u64 v[176:177], s[10:11], 0, v[2:3]
	v_and_b32_e32 v240, 63, v244
	s_lshl_b32 s100, s62, 2
	s_and_b32 s101, s62, 1
	s_lshl_b32 s101, s101, 3
	v_lshrrev_b32_e32 v241, 4, v240
	v_or_b32_e32 v242, s101, v241
	v_and_b32_e32 v243, 15, v240
	v_xor_b32_e32 v242, v243, v242
	v_add_u32_e32 v245, s100, v241
	v_mul_u32_u24_e32 v245, 0x2400, v245
	v_lshl_add_u32 v234, v242, 4, v245
	v_xor_b32_e32 v242, 4, v242
	v_add_u32_e32 v245, 0x9000, v245
	v_lshl_add_u32 v235, v242, 4, v245
	v_bfe_u32 v241, v240, 2, 3
	s_lshl_b32 s101, s62, 3
	v_or_b32_e32 v241, s101, v241
	v_mov_b32_e32 v242, v241
	v_subrev_u32_e32 v242, s100, v242
	v_mul_u32_u24_e32 v242, 0x2400, v242
	v_lshrrev_b32_e32 v243, 5, v240
	v_lshlrev_b32_e32 v243, 6, v243
	v_and_b32_e32 v245, 3, v240
	v_lshl_add_u32 v243, v245, 4, v243
	v_add_u32_e32 v236, v242, v243
	v_add_u32_e32 v236, 0x800, v236
	v_add_u32_e32 v237, 0x80, v236
	v_readfirstlane_b32 s100, v176
	v_readfirstlane_b32 s101, v177
	v_mov_b32_e32 v0, v205
	v_mov_b32_e32 v1, v205
	v_mov_b32_e32 v2, v205
	v_mov_b32_e32 v3, v205
	v_mov_b32_e32 v4, v205
	v_mov_b32_e32 v5, v205
	v_mov_b32_e32 v6, v205
	v_mov_b32_e32 v7, v205
	v_mov_b32_e32 v8, v205
	v_mov_b32_e32 v9, v205
	v_mov_b32_e32 v10, v205
	v_mov_b32_e32 v11, v205
	v_mov_b32_e32 v12, v205
	v_mov_b32_e32 v13, v205
	v_mov_b64_e32 v[62:63], v[14:15]
	v_mov_b64_e32 v[46:47], v[14:15]
	v_mov_b64_e32 v[30:31], v[14:15]
	s_mov_b32 s56, 0
	s_mov_b32 s57, 2
	v_mov_b32_e32 v65, v64
	v_mov_b32_e32 v66, v64
	v_mov_b32_e32 v67, v64
	v_mov_b32_e32 v68, v64
	v_mov_b32_e32 v69, v64
	v_mov_b32_e32 v70, v64
	v_mov_b32_e32 v71, v64
	v_mov_b32_e32 v72, v64
	v_mov_b32_e32 v73, v64
	v_mov_b32_e32 v74, v64
	v_mov_b32_e32 v75, v64
	v_mov_b32_e32 v76, v64
	v_mov_b32_e32 v77, v64
	v_mov_b32_e32 v78, v64
	v_mov_b32_e32 v79, v64
	s_add_i32 s19, s92, 0x9f
	v_lshl_add_u32 v186, v184, 2, s49
	s_sub_i32 s42, 0, s68
	v_mov_b32_e32 v187, 0
	v_mov_b32_e32 v203, 1.0
	s_mov_b32 s18, 0x10000
	s_mov_b32 s43, 0x8000
	v_mov_b64_e32 v[60:61], v[12:13]
	v_mov_b64_e32 v[58:59], v[10:11]
	v_mov_b64_e32 v[56:57], v[8:9]
	v_mov_b64_e32 v[54:55], v[6:7]
	v_mov_b64_e32 v[52:53], v[4:5]
	v_mov_b64_e32 v[50:51], v[2:3]
	v_mov_b64_e32 v[48:49], v[0:1]
	v_mov_b64_e32 v[44:45], v[12:13]
	v_mov_b64_e32 v[42:43], v[10:11]
	v_mov_b64_e32 v[40:41], v[8:9]
	v_mov_b64_e32 v[38:39], v[6:7]
	v_mov_b64_e32 v[36:37], v[4:5]
	v_mov_b64_e32 v[34:35], v[2:3]
	v_mov_b64_e32 v[32:33], v[0:1]
	v_mov_b64_e32 v[28:29], v[12:13]
	v_mov_b64_e32 v[26:27], v[10:11]
	v_mov_b64_e32 v[24:25], v[8:9]
	v_mov_b64_e32 v[22:23], v[6:7]
	v_mov_b64_e32 v[20:21], v[4:5]
	v_mov_b64_e32 v[18:19], v[2:3]
	v_mov_b64_e32 v[16:17], v[0:1]
	s_mov_b32 s10, 0
	s_waitcnt lgkmcnt(0)
	s_barrier

; __device__ __forceinline__ void finishSM(f32x16& p0, f32x16& p1, float alpha, float& l_reg, bf16x8& pa0, bf16x8& pa1, bf16x8& pa2, bf16x8& pa3) {
; #pragma unroll
;   for (int r = 0; r < 16; ++r) p1[r] = __builtin_amdgcn_exp2f(p1[r]);
;   float ps = 0;
; #pragma unroll
;   for (int r = 0; r < 16; ++r) ps += p0[r];
; #pragma unroll
;   for (int r = 0; r < 16; ++r) ps += p1[r];
;   { auto rr = __builtin_amdgcn_permlane32_swap(__float_as_uint(ps), __float_as_uint(ps), false, false);
;     ps = __uint_as_float(rr[0]) + __uint_as_float(rr[1]); }
;   l_reg = l_reg * alpha + ps;
;     ...
;   PK4(p0, 0, pa0); PK4(p0, 8, pa1); PK4(p1, 0, pa2); PK4(p1, 8, pa3);
;     ...
; }
.LBB0_166:
	s_add_i32 s34, s68, 0
	v_add_u32_e32 v96, s34, v188
	ds_read_b128 v[210:213], v96 offset:24576
	ds_read_b128 v[96:99], v96 offset:16384
	v_add_u32_e32 v201, s34, v196
	v_exp_f32_e32 v206, v81
	v_exp_f32_e32 v207, v82
	v_exp_f32_e32 v208, v83
	s_waitcnt lgkmcnt(0)
	v_mfma_f32_32x32x16_bf16 v[112:127], v[96:99], v[128:131], v[64:79]
	v_exp_f32_e32 v209, v84
	v_exp_f32_e32 v87, v87
	v_exp_f32_e32 v214, v88
	v_exp_f32_e32 v220, v93
	v_exp_f32_e32 v221, v94
	v_exp_f32_e32 v95, v95
	v_mfma_f32_32x32x16_bf16 v[96:111], v[210:213], v[128:131], v[64:79]
	ds_read_b128 v[210:213], v201 offset:24576
	ds_read_b128 v[216:219], v201 offset:16384
	v_add_u32_e32 v201, s34, v190
	s_waitcnt lgkmcnt(0)
	v_mfma_f32_32x32x16_bf16 v[112:127], v[216:219], v[132:135], v[112:127]
	v_mfma_f32_32x32x16_bf16 v[96:111], v[210:213], v[132:135], v[96:111]
	ds_read_b128 v[210:213], v201 offset:24576
	ds_read_b128 v[216:219], v201 offset:16384
	v_add_u32_e32 v201, s34, v189
	s_waitcnt lgkmcnt(0)
	v_mfma_f32_32x32x16_bf16 v[112:127], v[216:219], v[136:139], v[112:127]
	v_mfma_f32_32x32x16_bf16 v[96:111], v[210:213], v[136:139], v[96:111]
	ds_read_b128 v[210:213], v201 offset:24576
	ds_read_b128 v[216:219], v201 offset:16384
	v_exp_f32_e32 v201, v80
	v_pk_add_f32 v[144:145], v[160:161], v[162:163]
	v_pk_add_f32 v[144:145], v[144:145], v[164:165]
	v_pk_add_f32 v[144:145], v[144:145], v[166:167]
	v_pk_add_f32 v[144:145], v[144:145], v[168:169]
	v_pk_add_f32 v[144:145], v[144:145], v[170:171]
	v_pk_add_f32 v[144:145], v[144:145], v[172:173]
	v_pk_add_f32 v[144:145], v[144:145], v[174:175]
	v_pk_add_f32 v[144:145], v[144:145], v[206:207]
	v_pk_add_f32 v[144:145], v[144:145], v[208:209]
	v_pk_add_f32 v[144:145], v[144:145], v[220:221]
	v_add_f32_e32 v80, v87, v214
	v_add_f32_e32 v80, v95, v80
	s_waitcnt lgkmcnt(1)
	v_mfma_f32_32x32x16_bf16 v[96:111], v[210:213], v[140:143], v[96:111]
	v_exp_f32_e32 v212, v85
	v_add_f32_e32 v80, v201, v80
	v_exp_f32_e32 v213, v86
	s_waitcnt lgkmcnt(0)
	v_mfma_f32_32x32x16_bf16 v[112:127], v[216:219], v[140:143], v[112:127]
	v_exp_f32_e32 v216, v89
	v_exp_f32_e32 v217, v90
	v_exp_f32_e32 v218, v91
	v_exp_f32_e32 v219, v92
	v_pk_add_f32 v[144:145], v[144:145], v[212:213]
	v_pk_add_f32 v[144:145], v[144:145], v[216:217]
	v_pk_add_f32 v[144:145], v[144:145], v[218:219]
	v_add_f32_e32 v80, v144, v80
	v_add_f32_e32 v210, v145, v80
	v_mov_b32_e32 v211, v210
	v_cvt_pk_bf16_f32 v80, v173, v175
	v_cvt_pk_bf16_f32 v81, v171, v174
	v_cvt_pk_bf16_f32 v82, v169, v172
	v_cvt_pk_bf16_f32 v83, v168, v170
	v_cvt_pk_bf16_f32 v88, v165, v167
	v_cvt_pk_bf16_f32 v89, v163, v166
	v_cvt_pk_bf16_f32 v90, v161, v164
	v_cvt_pk_bf16_f32 v91, v160, v162
	v_cvt_pk_bf16_f32 v84, v201, v206
	v_cvt_pk_bf16_f32 v85, v207, v208
	v_cvt_pk_bf16_f32 v86, v209, v212
	v_cvt_pk_bf16_f32 v87, v213, v87
	v_cvt_pk_bf16_f32 v92, v214, v216
	v_cvt_pk_bf16_f32 v93, v217, v218
	v_cvt_pk_bf16_f32 v94, v219, v220
	v_cvt_pk_bf16_f32 v95, v221, v95
	s_nop 1
	v_permlane32_swap_b32_e32 v210, v211
	s_andn2_b64 vcc, exec, s[10:11]
	v_add_u32_e32 v212, s56, v202
	s_cbranch_vccnz .LBB0_168
	v_add_u32_e32 v160, 0xc0, v212
	v_med3_i32 v161, v160, 0, v249
	v_med3_i32 v160, v160, s75, v250
	v_lshl_add_u32 v162, v160, 2, s69
	v_add_u32_e32 v160, 0xc1, v212
	v_med3_i32 v163, v160, 0, v249
	v_med3_i32 v160, v160, s75, v250
	v_lshl_add_u32 v164, v160, 2, s69
	v_add_u32_e32 v160, 0xc2, v212
	v_med3_i32 v165, v160, 0, v249
	v_med3_i32 v160, v160, s75, v250
	v_lshl_add_u32 v166, v160, 2, s69
	v_add_u32_e32 v160, 0xc3, v212
	v_med3_i32 v167, v160, 0, v249
	v_med3_i32 v160, v160, s75, v250
	v_lshl_add_u32 v161, v161, 2, s69
	v_lshl_add_u32 v163, v163, 2, s69
	v_lshl_add_u32 v165, v165, 2, s69
	v_lshl_add_u32 v167, v167, 2, s69
	v_lshl_add_u32 v168, v160, 2, s69
	ds_read_b32 v160, v161
	ds_read_b32 v162, v162 offset:128
	ds_read_b32 v161, v163
	ds_read_b32 v163, v164 offset:128
	ds_read_b32 v164, v165
	ds_read_b32 v166, v166 offset:128
	ds_read_b32 v165, v167
	ds_read_b32 v167, v168 offset:128
	v_add_u32_e32 v168, 0xc8, v212
	v_med3_i32 v169, v168, 0, v249
	v_med3_i32 v168, v168, s75, v250
	v_lshl_add_u32 v170, v168, 2, s69
	v_add_u32_e32 v168, 0xc9, v212
	v_med3_i32 v171, v168, 0, v249
	v_med3_i32 v168, v168, s75, v250
	v_lshl_add_u32 v172, v168, 2, s69
	v_add_u32_e32 v168, 0xca, v212
	v_med3_i32 v173, v168, 0, v249
	v_med3_i32 v168, v168, s75, v250
	v_add_u32_e32 v207, 0xd1, v212
	v_lshl_add_u32 v174, v168, 2, s69
	v_add_u32_e32 v168, 0xcb, v212
	v_med3_i32 v208, v207, 0, v249
	v_med3_i32 v207, v207, s75, v250
	v_med3_i32 v175, v168, 0, v249
	v_med3_i32 v168, v168, s75, v250
	v_lshl_add_u32 v213, v207, 2, s69
	v_add_u32_e32 v207, 0xd2, v212
	v_lshl_add_u32 v169, v169, 2, s69
	v_lshl_add_u32 v171, v171, 2, s69
	v_lshl_add_u32 v173, v173, 2, s69
	v_lshl_add_u32 v175, v175, 2, s69
	v_lshl_add_u32 v201, v168, 2, s69
	v_lshl_add_u32 v209, v208, 2, s69
	v_med3_i32 v208, v207, 0, v249
	v_med3_i32 v207, v207, s75, v250
	ds_read_b32 v168, v169
	ds_read_b32 v170, v170 offset:128
	ds_read_b32 v169, v171
	ds_read_b32 v171, v172 offset:128
	ds_read_b32 v172, v173
	ds_read_b32 v174, v174 offset:128
	ds_read_b32 v173, v175
	ds_read_b32 v175, v201 offset:128
	v_add_u32_e32 v201, 0xd0, v212
	v_lshl_add_u32 v217, v207, 2, s69
	v_add_u32_e32 v207, 0xd3, v212
	v_med3_i32 v206, v201, 0, v249
	v_lshl_add_u32 v214, v208, 2, s69
	v_med3_i32 v208, v207, 0, v249
	v_med3_i32 v201, v201, s75, v250
	v_lshl_add_u32 v206, v206, 2, s69
	v_med3_i32 v207, v207, s75, v250
	v_lshl_add_u32 v219, v208, 2, s69
	v_lshl_add_u32 v201, v201, 2, s69
	v_lshl_add_u32 v220, v207, 2, s69
	ds_read_b32 v206, v206
	ds_read_b32 v208, v201 offset:128
	ds_read_b32 v207, v209
	ds_read_b32 v209, v213 offset:128
	ds_read_b32 v216, v214
	ds_read_b32 v218, v217 offset:128
	ds_read_b32 v217, v219
	ds_read_b32 v219, v220 offset:128
	v_add_u32_e32 v214, 0xd9, v212
	v_med3_i32 v220, v214, 0, v249
	v_lshl_add_u32 v221, v220, 2, s69
	v_add_u32_e32 v220, 0xda, v212
	v_med3_i32 v222, v220, 0, v249
	v_med3_i32 v220, v220, s75, v250
	v_add_u32_e32 v201, 0xd8, v212
	v_lshl_add_u32 v226, v220, 2, s69
	v_add_u32_e32 v220, 0xdb, v212
	v_med3_i32 v213, v201, 0, v249
	v_lshl_add_u32 v223, v222, 2, s69
	v_med3_i32 v222, v220, 0, v249
	v_med3_i32 v220, v220, s75, v250
	v_med3_i32 v201, v201, s75, v250
	v_lshl_add_u32 v213, v213, 2, s69
	v_med3_i32 v214, v214, s75, v250
	v_lshl_add_u32 v225, v222, 2, s69
	v_lshl_add_u32 v227, v220, 2, s69
	v_lshl_add_u32 v201, v201, 2, s69
	v_lshl_add_u32 v214, v214, 2, s69
	ds_read_b32 v220, v213
	ds_read_b32 v222, v201 offset:128
	ds_read_b32 v224, v223
	ds_read_b32 v225, v225
	ds_read_b32 v221, v221
	ds_read_b32 v227, v227 offset:128
	ds_read_b32 v226, v226 offset:128
	ds_read_b32 v223, v214 offset:128
	s_waitcnt lgkmcnt(4)
	v_pk_add_f32 v[126:127], v[126:127], v[224:225]
	s_waitcnt lgkmcnt(3)
	v_pk_add_f32 v[124:125], v[124:125], v[220:221]
	v_pk_add_f32 v[122:123], v[122:123], v[216:217]
	v_pk_add_f32 v[120:121], v[120:121], v[206:207]
	v_pk_add_f32 v[118:119], v[118:119], v[172:173]
	v_pk_add_f32 v[116:117], v[116:117], v[168:169]
	v_pk_add_f32 v[114:115], v[114:115], v[164:165]
	v_pk_add_f32 v[112:113], v[112:113], v[160:161]
	s_waitcnt lgkmcnt(1)
	v_pk_add_f32 v[110:111], v[110:111], v[226:227]
	s_waitcnt lgkmcnt(0)
	v_pk_add_f32 v[108:109], v[108:109], v[222:223]
	v_pk_add_f32 v[106:107], v[106:107], v[218:219]
	v_pk_add_f32 v[104:105], v[104:105], v[208:209]
	v_pk_add_f32 v[102:103], v[102:103], v[174:175]
	v_pk_add_f32 v[100:101], v[100:101], v[170:171]
	v_pk_add_f32 v[98:99], v[98:99], v[166:167]
	v_pk_add_f32 v[96:97], v[96:97], v[162:163]

; __device__ __forceinline__ void finishSM(f32x16& p0, f32x16& p1, float alpha, float& l_reg, bf16x8& pa0, bf16x8& pa1, bf16x8& pa2, bf16x8& pa3) {
; #pragma unroll
;   for (int r = 0; r < 16; ++r) p1[r] = __builtin_amdgcn_exp2f(p1[r]);
;   float ps = 0;
; #pragma unroll
;   for (int r = 0; r < 16; ++r) ps += p0[r];
; #pragma unroll
;   for (int r = 0; r < 16; ++r) ps += p1[r];
;   { auto rr = __builtin_amdgcn_permlane32_swap(__float_as_uint(ps), __float_as_uint(ps), false, false);
;     ps = __uint_as_float(rr[0]) + __uint_as_float(rr[1]); }
;   l_reg = l_reg * alpha + ps;
;     ...
;   PK4(p0, 0, pa0); PK4(p0, 8, pa1); PK4(p1, 0, pa2); PK4(p1, 8, pa3);
;     ...
; }
.LBB0_177:
	v_exp_f32_e32 v168, v112
	v_exp_f32_e32 v169, v113
	v_exp_f32_e32 v170, v114
	v_exp_f32_e32 v171, v115
	v_exp_f32_e32 v172, v116
	v_exp_f32_e32 v173, v117
	v_exp_f32_e32 v174, v118
	v_exp_f32_e32 v175, v119
	v_exp_f32_e32 v206, v120
	v_exp_f32_e32 v207, v121
	v_exp_f32_e32 v208, v122
	v_exp_f32_e32 v209, v123
	v_exp_f32_e32 v217, v124
	v_exp_f32_e32 v218, v125
	v_exp_f32_e32 v219, v126
	v_exp_f32_e32 v220, v127
	v_add_u32_e32 v80, s79, v188
	ds_read_b128 v[160:163], v80 offset:24576
	ds_read_b128 v[80:83], v80 offset:16384
	v_add_u32_e32 v164, s79, v196
	v_exp_f32_e32 v96, v96
	v_exp_f32_e32 v97, v97
	v_exp_f32_e32 v98, v98
	s_waitcnt lgkmcnt(0)
	v_mfma_f32_32x32x16_bf16 v[112:127], v[80:83], v[128:131], v[64:79]
	v_exp_f32_e32 v99, v99
	v_exp_f32_e32 v100, v100
	v_exp_f32_e32 v101, v101
	v_exp_f32_e32 v102, v102
	v_exp_f32_e32 v103, v103
	v_mfma_f32_32x32x16_bf16 v[80:95], v[160:163], v[128:131], v[64:79]
	ds_read_b128 v[160:163], v164 offset:24576
	ds_read_b128 v[164:167], v164 offset:16384
	s_waitcnt lgkmcnt(1)
	v_mfma_f32_32x32x16_bf16 v[80:95], v[160:163], v[132:135], v[80:95]
	s_waitcnt lgkmcnt(0)
	v_mfma_f32_32x32x16_bf16 v[112:127], v[164:167], v[132:135], v[112:127]
	v_add_u32_e32 v164, s79, v190
	ds_read_b128 v[160:163], v164 offset:24576
	ds_read_b128 v[164:167], v164 offset:16384
	s_waitcnt lgkmcnt(1)
	v_mfma_f32_32x32x16_bf16 v[80:95], v[160:163], v[136:139], v[80:95]
	s_waitcnt lgkmcnt(0)
	v_mfma_f32_32x32x16_bf16 v[112:127], v[164:167], v[136:139], v[112:127]
	v_add_u32_e32 v164, s79, v189
	ds_read_b128 v[160:163], v164 offset:24576
	ds_read_b128 v[164:167], v164 offset:16384
	s_waitcnt lgkmcnt(1)
	v_mfma_f32_32x32x16_bf16 v[80:95], v[160:163], v[140:143], v[80:95]
	v_exp_f32_e32 v160, v104
	v_pk_add_f32 v[144:145], v[168:169], v[170:171]
	v_pk_add_f32 v[144:145], v[144:145], v[172:173]
	v_pk_add_f32 v[144:145], v[144:145], v[174:175]
	v_pk_add_f32 v[144:145], v[144:145], v[206:207]
	v_pk_add_f32 v[144:145], v[144:145], v[208:209]
	v_pk_add_f32 v[144:145], v[144:145], v[218:219]
	v_pk_add_f32 v[144:145], v[144:145], v[96:97]
	v_pk_add_f32 v[144:145], v[144:145], v[98:99]
	v_pk_add_f32 v[144:145], v[144:145], v[100:101]
	v_exp_f32_e32 v161, v105
	v_pk_add_f32 v[144:145], v[144:145], v[102:103]
	v_exp_f32_e32 v162, v106
	v_add_f32_e32 v104, v217, v220
	v_exp_f32_e32 v163, v107
	s_waitcnt lgkmcnt(0)
	v_mfma_f32_32x32x16_bf16 v[112:127], v[164:167], v[140:143], v[112:127]
	v_exp_f32_e32 v164, v108
	v_exp_f32_e32 v165, v109
	v_exp_f32_e32 v166, v110
	v_exp_f32_e32 v167, v111
	v_pk_add_f32 v[144:145], v[144:145], v[160:161]
	v_pk_add_f32 v[144:145], v[144:145], v[162:163]
	v_pk_add_f32 v[144:145], v[144:145], v[164:165]
	v_pk_add_f32 v[144:145], v[144:145], v[166:167]
	v_add_f32_e32 v104, v144, v104
	v_add_f32_e32 v215, v145, v104
	v_mov_b32_e32 v216, v215
	v_cvt_pk_bf16_f32 v104, v168, v169
	v_cvt_pk_bf16_f32 v105, v170, v171
	v_cvt_pk_bf16_f32 v106, v172, v173
	v_cvt_pk_bf16_f32 v107, v174, v175
	v_cvt_pk_bf16_f32 v108, v206, v207
	v_cvt_pk_bf16_f32 v109, v208, v209
	v_cvt_pk_bf16_f32 v110, v217, v218
	v_cvt_pk_bf16_f32 v111, v219, v220
	v_cvt_pk_bf16_f32 v96, v96, v97
	v_cvt_pk_bf16_f32 v97, v98, v99
	v_cvt_pk_bf16_f32 v98, v100, v101
	v_cvt_pk_bf16_f32 v99, v102, v103
	v_cvt_pk_bf16_f32 v100, v160, v161
	v_cvt_pk_bf16_f32 v101, v162, v163
	v_cvt_pk_bf16_f32 v102, v164, v165
	v_cvt_pk_bf16_f32 v103, v166, v167
	s_nop 1
	v_permlane32_swap_b32_e32 v215, v216
	s_andn2_b64 vcc, exec, s[10:11]
	s_cbranch_vccnz .LBB0_179
	v_add_u32_e32 v160, 0x100, v212
	v_med3_i32 v161, v160, 0, v249
	v_med3_i32 v160, v160, s75, v250
	v_lshl_add_u32 v162, v160, 2, s69
	v_add_u32_e32 v160, 0x101, v212
	v_med3_i32 v163, v160, 0, v249
	v_med3_i32 v160, v160, s75, v250
	v_lshl_add_u32 v164, v160, 2, s69
	v_add_u32_e32 v160, 0x102, v212
	v_med3_i32 v165, v160, 0, v249
	v_med3_i32 v160, v160, s75, v250
	v_lshl_add_u32 v166, v160, 2, s69
	v_add_u32_e32 v160, 0x103, v212
	v_med3_i32 v167, v160, 0, v249
	v_med3_i32 v160, v160, s75, v250
	v_lshl_add_u32 v161, v161, 2, s69
	v_lshl_add_u32 v163, v163, 2, s69
	v_lshl_add_u32 v165, v165, 2, s69
	v_lshl_add_u32 v167, v167, 2, s69
	v_lshl_add_u32 v168, v160, 2, s69
	ds_read_b32 v160, v161
	ds_read_b32 v162, v162 offset:128
	ds_read_b32 v161, v163
	ds_read_b32 v163, v164 offset:128
	ds_read_b32 v164, v165
	ds_read_b32 v166, v166 offset:128
	ds_read_b32 v165, v167
	ds_read_b32 v167, v168 offset:128
	v_add_u32_e32 v168, 0x108, v212
	v_med3_i32 v169, v168, 0, v249
	v_med3_i32 v168, v168, s75, v250
	v_lshl_add_u32 v170, v168, 2, s69
	v_add_u32_e32 v168, 0x109, v212
	v_med3_i32 v171, v168, 0, v249
	v_med3_i32 v168, v168, s75, v250
	v_lshl_add_u32 v172, v168, 2, s69
	v_add_u32_e32 v168, 0x10a, v212
	v_med3_i32 v173, v168, 0, v249
	v_med3_i32 v168, v168, s75, v250
	v_lshl_add_u32 v174, v168, 2, s69
	v_add_u32_e32 v168, 0x10b, v212
	v_med3_i32 v175, v168, 0, v249
	v_med3_i32 v168, v168, s75, v250
	v_lshl_add_u32 v169, v169, 2, s69
	v_lshl_add_u32 v171, v171, 2, s69
	v_lshl_add_u32 v173, v173, 2, s69
	v_lshl_add_u32 v175, v175, 2, s69
	v_lshl_add_u32 v206, v168, 2, s69
	ds_read_b32 v168, v169
	ds_read_b32 v170, v170 offset:128
	ds_read_b32 v169, v171
	ds_read_b32 v171, v172 offset:128
	ds_read_b32 v172, v173
	ds_read_b32 v174, v174 offset:128
	ds_read_b32 v173, v175
	ds_read_b32 v175, v206 offset:128
	v_add_u32_e32 v206, 0x110, v212
	v_med3_i32 v207, v206, 0, v249
	v_med3_i32 v206, v206, s75, v250
	v_lshl_add_u32 v208, v206, 2, s69
	v_add_u32_e32 v206, 0x111, v212
	v_med3_i32 v209, v206, 0, v249
	v_med3_i32 v206, v206, s75, v250
	v_lshl_add_u32 v217, v206, 2, s69
	v_add_u32_e32 v206, 0x112, v212
	v_med3_i32 v218, v206, 0, v249
	v_med3_i32 v206, v206, s75, v250
	v_lshl_add_u32 v219, v206, 2, s69
	v_add_u32_e32 v206, 0x113, v212
	v_add_u32_e32 v223, 0x119, v212
	v_med3_i32 v220, v206, 0, v249
	v_med3_i32 v224, v223, 0, v249
	v_med3_i32 v223, v223, s75, v250
	v_lshl_add_u32 v207, v207, 2, s69
	v_lshl_add_u32 v209, v209, 2, s69
	v_lshl_add_u32 v218, v218, 2, s69
	v_med3_i32 v206, v206, s75, v250
	v_lshl_add_u32 v221, v220, 2, s69
	v_lshl_add_u32 v230, v223, 2, s69
	v_add_u32_e32 v223, 0x11a, v212
	v_lshl_add_u32 v222, v206, 2, s69
	ds_read_b32 v206, v207
	ds_read_b32 v208, v208 offset:128
	ds_read_b32 v207, v209
	ds_read_b32 v209, v217 offset:128
	ds_read_b32 v218, v218
	ds_read_b32 v220, v219 offset:128
	ds_read_b32 v219, v221
	ds_read_b32 v221, v222 offset:128
	v_add_u32_e32 v217, 0x118, v212
	v_lshl_add_u32 v225, v224, 2, s69
	v_med3_i32 v224, v223, 0, v249
	v_med3_i32 v223, v223, s75, v250
	v_add_u32_e32 v212, 0x11b, v212
	v_med3_i32 v222, v217, 0, v249
	v_lshl_add_u32 v228, v223, 2, s69
	v_med3_i32 v223, v212, 0, v249
	v_med3_i32 v217, v217, s75, v250
	v_lshl_add_u32 v222, v222, 2, s69
	v_lshl_add_u32 v226, v224, 2, s69
	v_med3_i32 v212, v212, s75, v250
	v_lshl_add_u32 v223, v223, 2, s69
	v_lshl_add_u32 v217, v217, 2, s69
	v_lshl_add_u32 v212, v212, 2, s69
	ds_read_b32 v222, v222
	ds_read_b32 v224, v217 offset:128
	ds_read_b32 v226, v226
	ds_read_b32 v227, v223
	ds_read_b32 v223, v225
	ds_read_b32 v229, v212 offset:128
	ds_read_b32 v228, v228 offset:128
	ds_read_b32 v225, v230 offset:128
	s_waitcnt lgkmcnt(4)
	v_pk_add_f32 v[126:127], v[126:127], v[226:227]
	s_waitcnt lgkmcnt(3)
	v_pk_add_f32 v[124:125], v[124:125], v[222:223]
	v_pk_add_f32 v[122:123], v[122:123], v[218:219]
	v_pk_add_f32 v[120:121], v[120:121], v[206:207]
	v_pk_add_f32 v[118:119], v[118:119], v[172:173]
	v_pk_add_f32 v[116:117], v[116:117], v[168:169]
	v_pk_add_f32 v[114:115], v[114:115], v[164:165]
	v_pk_add_f32 v[112:113], v[112:113], v[160:161]
	s_waitcnt lgkmcnt(1)
	v_pk_add_f32 v[94:95], v[94:95], v[228:229]
	s_waitcnt lgkmcnt(0)
	v_pk_add_f32 v[92:93], v[92:93], v[224:225]
	v_pk_add_f32 v[90:91], v[90:91], v[220:221]
	v_pk_add_f32 v[88:89], v[88:89], v[208:209]
	v_pk_add_f32 v[86:87], v[86:87], v[174:175]
	v_pk_add_f32 v[84:85], v[84:85], v[170:171]
	v_pk_add_f32 v[82:83], v[82:83], v[166:167]
	v_pk_add_f32 v[80:81], v[80:81], v[162:163]

; __device__ __forceinline__ unsigned cvtpk(float lo, float hi) { unsigned r; asm volatile("v_cvt_pk_bf16_f32 %0, %1, %2" : "=v"(r) : "v"(lo), "v"(hi)); return r; }
; __device__ __forceinline__ void finishSM(f32x16& p0, f32x16& p1, float alpha, float& l_reg, bf16x8& pa0, bf16x8& pa1, bf16x8& pa2, bf16x8& pa3) {
; #pragma unroll
;   for (int r = 0; r < 16; ++r) p1[r] = __builtin_amdgcn_exp2f(p1[r]);
;   float ps = 0;
; #pragma unroll
;   for (int r = 0; r < 16; ++r) ps += p0[r];
; #pragma unroll
;   for (int r = 0; r < 16; ++r) ps += p1[r];
;   { auto rr = __builtin_amdgcn_permlane32_swap(__float_as_uint(ps), __float_as_uint(ps), false, false);
;     ps = __uint_as_float(rr[0]) + __uint_as_float(rr[1]); }
;   l_reg = l_reg * alpha + ps;
;     ...
;   PK4(p0, 0, pa0); PK4(p0, 8, pa1); PK4(p1, 0, pa2); PK4(p1, 8, pa3);
;     ...
; }
; __device__ __forceinline__ bf16x8 scale_bf16x8(bf16x8 v, float c) {
;   u32x4 w = *reinterpret_cast<u32x4*>(&v), o;
; #pragma unroll
;   for (int i = 0; i < 4; ++i) { const float lo = __uint_as_float(w[i] << 16), hh = __uint_as_float(w[i] & 0xffff0000u); o[i] = cvtpk(lo * c, hh * c); }
;   return *reinterpret_cast<bf16x8*>(&o);
; }
; template <int ND0> __device__ __forceinline__ void qkt(f32x16& p0, f32x16& p1, const char* Ks, const bf16x8* qr, int r32, int hi, int cboff, const f32x16& ci) {
; #pragma unroll
;   for (int d0 = 0; d0 < ND0; ++d0) { int cb = cboff + (d0 * 16 + hi * 8) * 2;
;     bf16x8 b0 = *reinterpret_cast<const bf16x8*>(Ks + KSWZ(r32, cb));
;     bf16x8 b1 = *reinterpret_cast<const bf16x8*>(Ks + KSWZ(32 + r32, cb));
;     if (d0 == 0) { p0 = __builtin_amdgcn_mfma_f32_32x32x16_bf16(b0, qr[0], ci, 0, 0, 0); p1 = __builtin_amdgcn_mfma_f32_32x32x16_bf16(b1, qr[0], ci, 0, 0, 0); }
;     else { p0 = __builtin_amdgcn_mfma_f32_32x32x16_bf16(b0, qr[d0], p0, 0, 0, 0); p1 = __builtin_amdgcn_mfma_f32_32x32x16_bf16(b1, qr[d0], p1, 0, 0, 0); } }
; }
.LBB0_191:
	v_add_u32_e32 v96, s78, v188
	ds_read_b128 v[112:115], v96 offset:24576
	ds_read_b128 v[116:119], v96 offset:16384
	v_exp_f32_e32 v120, v88
	v_exp_f32_e32 v121, v89
	v_exp_f32_e32 v122, v90
	v_exp_f32_e32 v123, v91
	s_waitcnt lgkmcnt(0)
	v_mfma_f32_32x32x16_bf16 v[96:111], v[116:119], v[128:131], v[64:79]
	v_add_u32_e32 v116, s78, v196
	v_exp_f32_e32 v124, v92
	v_exp_f32_e32 v125, v93
	v_exp_f32_e32 v126, v94
	v_exp_f32_e32 v95, v95
	v_mfma_f32_32x32x16_bf16 v[64:79], v[112:115], v[128:131], v[64:79]
	ds_read_b128 v[112:115], v116 offset:24576
	ds_read_b128 v[116:119], v116 offset:16384
	s_waitcnt lgkmcnt(1)
	v_mfma_f32_32x32x16_bf16 v[64:79], v[112:115], v[132:135], v[64:79]
	s_waitcnt lgkmcnt(0)
	v_mfma_f32_32x32x16_bf16 v[96:111], v[116:119], v[132:135], v[96:111]
	v_add_u32_e32 v116, s78, v190
	ds_read_b128 v[112:115], v116 offset:24576
	ds_read_b128 v[116:119], v116 offset:16384
	s_waitcnt lgkmcnt(1)
	v_mfma_f32_32x32x16_bf16 v[64:79], v[112:115], v[136:139], v[64:79]
	s_waitcnt lgkmcnt(0)
	v_mfma_f32_32x32x16_bf16 v[96:111], v[116:119], v[136:139], v[96:111]
	v_add_u32_e32 v116, s78, v189
	ds_read_b128 v[112:115], v116 offset:24576
	ds_read_b128 v[116:119], v116 offset:16384
	s_waitcnt lgkmcnt(1)
	v_mfma_f32_32x32x16_bf16 v[64:79], v[112:115], v[140:143], v[64:79]
	v_exp_f32_e32 v112, v80
	v_add_f32_e32 v80, 0, v173
	v_add_f32_e32 v80, v175, v80
	v_add_f32_e32 v80, v171, v80
	v_add_f32_e32 v80, v174, v80
	v_add_f32_e32 v80, v169, v80
	v_add_f32_e32 v80, v172, v80
	v_add_f32_e32 v80, v168, v80
	v_add_f32_e32 v80, v170, v80
	v_add_f32_e32 v80, v165, v80
	v_add_f32_e32 v80, v167, v80
	v_add_f32_e32 v80, v163, v80
	v_add_f32_e32 v80, v166, v80
	v_add_f32_e32 v80, v161, v80
	v_exp_f32_e32 v113, v81
	v_add_f32_e32 v80, v164, v80
	v_exp_f32_e32 v114, v82
	v_add_f32_e32 v80, v160, v80
	v_exp_f32_e32 v115, v83
	v_add_f32_e32 v80, v162, v80
	s_waitcnt lgkmcnt(0)
	v_mfma_f32_32x32x16_bf16 v[96:111], v[116:119], v[140:143], v[96:111]
	v_exp_f32_e32 v116, v84
	v_add_f32_e32 v80, v112, v80
	v_exp_f32_e32 v117, v85
	v_add_f32_e32 v80, v113, v80
	v_exp_f32_e32 v118, v86
	v_add_f32_e32 v80, v114, v80
	v_exp_f32_e32 v119, v87
	v_add_f32_e32 v80, v115, v80
	v_add_f32_e32 v80, v116, v80
	v_add_f32_e32 v80, v117, v80
	v_add_f32_e32 v80, v118, v80
	v_add_f32_e32 v80, v119, v80
	v_add_f32_e32 v80, v120, v80
	v_add_f32_e32 v80, v121, v80
	v_add_f32_e32 v80, v122, v80
	v_add_f32_e32 v80, v123, v80
	v_add_f32_e32 v80, v124, v80
	v_add_f32_e32 v80, v125, v80
	v_add_f32_e32 v80, v126, v80
	v_add_f32_e32 v128, v95, v80
	v_mov_b32_e32 v129, v128
	v_cvt_pk_bf16_f32 v80, v173, v175
	v_cvt_pk_bf16_f32 v81, v171, v174
	v_cvt_pk_bf16_f32 v82, v169, v172
	v_cvt_pk_bf16_f32 v83, v168, v170
	v_cvt_pk_bf16_f32 v84, v165, v167
	v_cvt_pk_bf16_f32 v85, v163, v166
	v_cvt_pk_bf16_f32 v86, v161, v164
	v_cvt_pk_bf16_f32 v87, v160, v162
	v_cvt_pk_bf16_f32 v88, v112, v113
	v_cvt_pk_bf16_f32 v89, v114, v115
	v_cvt_pk_bf16_f32 v90, v116, v117
	v_cvt_pk_bf16_f32 v91, v118, v119
	v_cvt_pk_bf16_f32 v92, v120, v121
	v_cvt_pk_bf16_f32 v93, v122, v123
	v_cvt_pk_bf16_f32 v94, v124, v125
	v_cvt_pk_bf16_f32 v95, v126, v95
	s_nop 1
	v_permlane32_swap_b32_e32 v128, v129
	s_andn2_b64 vcc, exec, s[10:11]
	s_cbranch_vccnz .LBB0_193
	v_or3_b32 v112, s19, v197, 64
	v_sub_u32_e32 v138, v112, v198
	v_add_u32_e32 v114, 1, v138
	v_med3_i32 v115, v114, 0, v249
	v_med3_i32 v114, v114, s75, v250
	v_lshl_add_u32 v116, v114, 2, s69
	v_add_u32_e32 v114, 2, v138
	v_med3_i32 v117, v114, 0, v249
	v_med3_i32 v114, v114, s75, v250
	v_lshl_add_u32 v118, v114, 2, s69
	v_add_u32_e32 v114, 3, v138
	v_med3_i32 v112, v138, 0, v249
	v_med3_i32 v113, v138, s75, v250
	v_med3_i32 v119, v114, 0, v249
	v_med3_i32 v114, v114, s75, v250
	v_lshl_add_u32 v112, v112, 2, s69
	v_lshl_add_u32 v113, v113, 2, s69
	v_lshl_add_u32 v115, v115, 2, s69
	v_lshl_add_u32 v117, v117, 2, s69
	v_lshl_add_u32 v119, v119, 2, s69
	v_lshl_add_u32 v120, v114, 2, s69
	ds_read_b32 v112, v112
	ds_read_b32 v114, v113 offset:128
	ds_read_b32 v113, v115
	ds_read_b32 v115, v116 offset:128
	ds_read_b32 v116, v117
	ds_read_b32 v118, v118 offset:128
	ds_read_b32 v117, v119
	ds_read_b32 v119, v120 offset:128
	v_add_u32_e32 v120, 8, v138
	v_med3_i32 v121, v120, 0, v249
	v_med3_i32 v120, v120, s75, v250
	v_lshl_add_u32 v122, v120, 2, s69
	v_add_u32_e32 v120, 9, v138
	v_med3_i32 v123, v120, 0, v249
	v_med3_i32 v120, v120, s75, v250
	v_lshl_add_u32 v124, v120, 2, s69
	v_add_u32_e32 v120, 10, v138
	v_med3_i32 v125, v120, 0, v249
	v_med3_i32 v120, v120, s75, v250
	v_lshl_add_u32 v126, v120, 2, s69
	v_add_u32_e32 v120, 11, v138
	v_med3_i32 v127, v120, 0, v249
	v_med3_i32 v120, v120, s75, v250
	v_lshl_add_u32 v121, v121, 2, s69
	v_lshl_add_u32 v123, v123, 2, s69
	v_lshl_add_u32 v125, v125, 2, s69
	v_lshl_add_u32 v127, v127, 2, s69
	v_lshl_add_u32 v130, v120, 2, s69
	ds_read_b32 v120, v121
	ds_read_b32 v122, v122 offset:128
	ds_read_b32 v121, v123
	ds_read_b32 v123, v124 offset:128
	ds_read_b32 v124, v125
	ds_read_b32 v126, v126 offset:128
	ds_read_b32 v125, v127
	ds_read_b32 v127, v130 offset:128
	v_add_u32_e32 v130, 16, v138
	v_med3_i32 v131, v130, 0, v249
	v_med3_i32 v130, v130, s75, v250
	v_lshl_add_u32 v132, v130, 2, s69
	v_add_u32_e32 v130, 17, v138
	v_med3_i32 v133, v130, 0, v249
	v_med3_i32 v130, v130, s75, v250
	v_lshl_add_u32 v134, v130, 2, s69
	v_add_u32_e32 v130, 18, v138
	v_med3_i32 v135, v130, 0, v249
	v_med3_i32 v130, v130, s75, v250
	v_lshl_add_u32 v136, v130, 2, s69
	v_add_u32_e32 v130, 19, v138
	v_add_u32_e32 v141, 25, v138
	v_med3_i32 v137, v130, 0, v249
	v_med3_i32 v130, v130, s75, v250
	v_med3_i32 v142, v141, 0, v249
	v_lshl_add_u32 v131, v131, 2, s69
	v_lshl_add_u32 v133, v133, 2, s69
	v_lshl_add_u32 v135, v135, 2, s69
	v_lshl_add_u32 v137, v137, 2, s69
	v_lshl_add_u32 v139, v130, 2, s69
	v_lshl_add_u32 v144, v142, 2, s69
	v_add_u32_e32 v142, 26, v138
	ds_read_b32 v130, v131
	ds_read_b32 v132, v132 offset:128
	ds_read_b32 v131, v133
	ds_read_b32 v133, v134 offset:128
	ds_read_b32 v134, v135
	ds_read_b32 v136, v136 offset:128
	ds_read_b32 v135, v137
	ds_read_b32 v137, v139 offset:128
	v_add_u32_e32 v139, 24, v138
	v_med3_i32 v143, v142, 0, v249
	v_med3_i32 v142, v142, s75, v250
	v_add_u32_e32 v138, 27, v138
	v_med3_i32 v140, v139, 0, v249
	v_med3_i32 v139, v139, s75, v250
	v_med3_i32 v141, v141, s75, v250
	v_lshl_add_u32 v146, v142, 2, s69
	v_med3_i32 v142, v138, 0, v249
	v_lshl_add_u32 v140, v140, 2, s69
	v_lshl_add_u32 v139, v139, 2, s69
	v_lshl_add_u32 v141, v141, 2, s69
	v_lshl_add_u32 v143, v143, 2, s69
	v_med3_i32 v138, v138, s75, v250
	v_lshl_add_u32 v145, v142, 2, s69
	v_lshl_add_u32 v147, v138, 2, s69
	ds_read_b32 v138, v140
	ds_read_b32 v140, v139 offset:128
	ds_read_b32 v142, v143
	ds_read_b32 v143, v145
	ds_read_b32 v139, v144
	ds_read_b32 v145, v147 offset:128
	ds_read_b32 v144, v146 offset:128
	ds_read_b32 v141, v141 offset:128
	s_waitcnt lgkmcnt(4)
	v_pk_add_f32 v[110:111], v[110:111], v[142:143]
	s_waitcnt lgkmcnt(3)
	v_pk_add_f32 v[108:109], v[108:109], v[138:139]
	v_pk_add_f32 v[106:107], v[106:107], v[134:135]
	v_pk_add_f32 v[104:105], v[104:105], v[130:131]
	v_pk_add_f32 v[102:103], v[102:103], v[124:125]
	v_pk_add_f32 v[100:101], v[100:101], v[120:121]
	v_pk_add_f32 v[98:99], v[98:99], v[116:117]
	v_pk_add_f32 v[96:97], v[96:97], v[112:113]
	s_waitcnt lgkmcnt(1)
	v_pk_add_f32 v[78:79], v[78:79], v[144:145]
	s_waitcnt lgkmcnt(0)
	v_pk_add_f32 v[76:77], v[76:77], v[140:141]
	v_pk_add_f32 v[74:75], v[74:75], v[136:137]
	v_pk_add_f32 v[72:73], v[72:73], v[132:133]
	v_pk_add_f32 v[70:71], v[70:71], v[126:127]
	v_pk_add_f32 v[68:69], v[68:69], v[122:123]
	v_pk_add_f32 v[66:67], v[66:67], v[118:119]
	v_pk_add_f32 v[64:65], v[64:65], v[114:115]

; #define SBAR() __builtin_amdgcn_sched_barrier(0)
; __device__ __forceinline__ int crow(int r, int hi) { return (r & 3) + 8 * (r >> 2) + 4 * hi; }
; #define RESC(a) do { if (__any((a) < 1.f)) { if (hi == 0) al_l[r32] = (a); asm volatile("s_waitcnt lgkmcnt(0)" ::: "memory"); \
;     _Pragma("unroll") for (int d = 0; d < 4; ++d) _Pragma("unroll") for (int r = 0; r < 16; ++r) o[d][r] *= al_l[crow(r, hi)]; } } while (0)
; template <int MODE, int ORD> ...
;     ...
;   RESC(alB);
;   finishSM(pB0, pB1, alB, l_reg, pa0, pa1, pa2, pa3); SBAR();
;   pv_d0(o, vb0 + oc, pa0, pa1, pa2, pa3);
;     ...
;   if (hi == 0) li_l[r32] = l_reg; asm volatile("s_waitcnt lgkmcnt(0)" ::: "memory");
;   float rli[16];
; #pragma unroll
;   for (int r = 0; r < 16; ++r) rli[r] = __builtin_amdgcn_rcpf(li_l[crow(r, hi)]);
.LBB0_199:
	v_exp_f32_e32 v80, v96
	v_exp_f32_e32 v81, v97
	v_exp_f32_e32 v82, v98
	v_exp_f32_e32 v83, v99
	v_exp_f32_e32 v84, v100
	v_exp_f32_e32 v96, v64
	v_add_f32_e32 v64, 0, v80
	v_exp_f32_e32 v85, v101
	v_add_f32_e32 v64, v81, v64
	v_exp_f32_e32 v86, v102
	v_add_f32_e32 v64, v82, v64
	v_exp_f32_e32 v87, v103
	v_add_f32_e32 v64, v83, v64
	v_exp_f32_e32 v88, v104
	v_add_f32_e32 v64, v84, v64
	v_exp_f32_e32 v89, v105
	v_add_f32_e32 v64, v85, v64
	v_exp_f32_e32 v90, v106
	v_add_f32_e32 v64, v86, v64
	v_exp_f32_e32 v91, v107
	v_add_f32_e32 v64, v87, v64
	v_exp_f32_e32 v92, v108
	v_add_f32_e32 v64, v88, v64
	v_exp_f32_e32 v93, v109
	v_add_f32_e32 v64, v89, v64
	v_exp_f32_e32 v94, v110
	v_add_f32_e32 v64, v90, v64
	v_exp_f32_e32 v95, v111
	v_add_f32_e32 v64, v91, v64
	v_add_f32_e32 v64, v92, v64
	v_exp_f32_e32 v97, v65
	v_add_f32_e32 v64, v93, v64
	v_exp_f32_e32 v98, v66
	v_add_f32_e32 v64, v94, v64
	v_exp_f32_e32 v99, v67
	v_add_f32_e32 v64, v95, v64
	v_exp_f32_e32 v100, v68
	v_add_f32_e32 v64, v96, v64
	v_exp_f32_e32 v101, v69
	v_add_f32_e32 v64, v97, v64
	v_exp_f32_e32 v102, v70
	v_add_f32_e32 v64, v98, v64
	v_exp_f32_e32 v103, v71
	v_add_f32_e32 v64, v99, v64
	v_exp_f32_e32 v104, v72
	v_add_f32_e32 v64, v100, v64
	v_exp_f32_e32 v105, v73
	v_add_f32_e32 v64, v101, v64
	v_exp_f32_e32 v106, v74
	v_add_f32_e32 v64, v102, v64
	v_exp_f32_e32 v107, v75
	v_add_f32_e32 v64, v103, v64
	v_exp_f32_e32 v108, v76
	v_add_f32_e32 v64, v104, v64
	v_exp_f32_e32 v109, v77
	v_add_f32_e32 v64, v105, v64
	v_exp_f32_e32 v110, v78
	v_add_f32_e32 v64, v106, v64
	v_exp_f32_e32 v111, v79
	v_add_f32_e32 v64, v107, v64
	v_add_f32_e32 v64, v108, v64
	v_add_f32_e32 v64, v109, v64
	v_add_f32_e32 v64, v110, v64
	v_add_f32_e32 v64, v111, v64
	v_mov_b32_e32 v65, v64
	s_nop 1
	v_permlane32_swap_b32_e32 v64, v65
	v_cvt_pk_bf16_f32 v66, v80, v81
	v_cvt_pk_bf16_f32 v67, v82, v83
	v_cvt_pk_bf16_f32 v68, v84, v85
	v_cvt_pk_bf16_f32 v69, v86, v87
	v_cvt_pk_bf16_f32 v70, v88, v89
	v_cvt_pk_bf16_f32 v71, v90, v91
	v_cvt_pk_bf16_f32 v72, v92, v93
	v_cvt_pk_bf16_f32 v73, v94, v95
	v_cvt_pk_bf16_f32 v74, v96, v97
	v_cvt_pk_bf16_f32 v75, v98, v99
	v_cvt_pk_bf16_f32 v76, v100, v101
	v_cvt_pk_bf16_f32 v77, v102, v103
	v_cvt_pk_bf16_f32 v78, v104, v105
	v_cvt_pk_bf16_f32 v79, v106, v107
	v_cvt_pk_bf16_f32 v80, v108, v109
	v_cvt_pk_bf16_f32 v81, v110, v111
	s_nop 0
	ds_read_b64_tr_b16 v[82:83], v201 offset:0
	ds_read_b64_tr_b16 v[84:85], v201 offset:0x800
	ds_read_b64_tr_b16 v[86:87], v201 offset:0x1000
	ds_read_b64_tr_b16 v[88:89], v201 offset:0x1800
	ds_read_b64_tr_b16 v[90:91], v201 offset:0x2000
	ds_read_b64_tr_b16 v[92:93], v201 offset:0x2800
	ds_read_b64_tr_b16 v[94:95], v201 offset:0x3000
	ds_read_b64_tr_b16 v[96:97], v201 offset:0x3800
	ds_read_b64_tr_b16 v[98:99], v201 offset:0x200
	ds_read_b64_tr_b16 v[100:101], v201 offset:0xa00
	ds_read_b64_tr_b16 v[102:103], v201 offset:0x1200
	ds_read_b64_tr_b16 v[104:105], v201 offset:0x1a00
	ds_read_b64_tr_b16 v[106:107], v201 offset:0x2200
	ds_read_b64_tr_b16 v[108:109], v201 offset:0x2a00
	ds_read_b64_tr_b16 v[110:111], v201 offset:0x3200
	ds_read_b64_tr_b16 v[112:113], v201 offset:0x3a00
	s_waitcnt lgkmcnt(8)
	s_nop 0
	v_mfma_f32_32x32x16_bf16 v[0:15], v[66:69], v[82:85], v[0:15]
	v_mfma_f32_32x32x16_bf16 v[0:15], v[70:73], v[86:89], v[0:15]
	v_mfma_f32_32x32x16_bf16 v[0:15], v[74:77], v[90:93], v[0:15]
	v_mfma_f32_32x32x16_bf16 v[0:15], v[78:81], v[94:97], v[0:15]
	ds_read_b64_tr_b16 v[82:83], v201 offset:0x400
	ds_read_b64_tr_b16 v[84:85], v201 offset:0xc00
	ds_read_b64_tr_b16 v[86:87], v201 offset:0x1400
	ds_read_b64_tr_b16 v[88:89], v201 offset:0x1c00
	ds_read_b64_tr_b16 v[90:91], v201 offset:0x2400
	ds_read_b64_tr_b16 v[92:93], v201 offset:0x2c00
	ds_read_b64_tr_b16 v[94:95], v201 offset:0x3400
	ds_read_b64_tr_b16 v[96:97], v201 offset:0x3c00
	s_waitcnt lgkmcnt(8)
	v_mfma_f32_32x32x16_bf16 v[48:63], v[66:69], v[98:101], v[48:63]
	v_mfma_f32_32x32x16_bf16 v[48:63], v[70:73], v[102:105], v[48:63]
	v_mfma_f32_32x32x16_bf16 v[48:63], v[74:77], v[106:109], v[48:63]
	v_mfma_f32_32x32x16_bf16 v[48:63], v[78:81], v[110:113], v[48:63]
	ds_read_b64_tr_b16 v[98:99], v201 offset:0x600
	ds_read_b64_tr_b16 v[100:101], v201 offset:0xe00
	ds_read_b64_tr_b16 v[102:103], v201 offset:0x1600
	ds_read_b64_tr_b16 v[104:105], v201 offset:0x1e00
	ds_read_b64_tr_b16 v[106:107], v201 offset:0x2600
	ds_read_b64_tr_b16 v[108:109], v201 offset:0x2e00
	ds_read_b64_tr_b16 v[110:111], v201 offset:0x3600
	ds_read_b64_tr_b16 v[112:113], v201 offset:0x3e00
	s_waitcnt lgkmcnt(8)
	v_mfma_f32_32x32x16_bf16 v[32:47], v[66:69], v[82:85], v[32:47]
	v_mfma_f32_32x32x16_bf16 v[32:47], v[70:73], v[86:89], v[32:47]
	v_mfma_f32_32x32x16_bf16 v[32:47], v[74:77], v[90:93], v[32:47]
	v_mfma_f32_32x32x16_bf16 v[32:47], v[78:81], v[94:97], v[32:47]
	s_waitcnt lgkmcnt(0)
	v_mfma_f32_32x32x16_bf16 v[16:31], v[66:69], v[98:101], v[16:31]
	v_mfma_f32_32x32x16_bf16 v[16:31], v[70:73], v[102:105], v[16:31]
	v_mfma_f32_32x32x16_bf16 v[16:31], v[74:77], v[106:109], v[16:31]
	v_mfma_f32_32x32x16_bf16 v[16:31], v[78:81], v[110:113], v[16:31]
	s_and_saveexec_b64 s[10:11], s[0:1]
	v_add_f32_e32 v66, v128, v129
	v_fmac_f32_e32 v66, v187, v212
	v_add_f32_e32 v64, v64, v65
	v_fmac_f32_e32 v64, v66, v130
	ds_write_b32 v186, v64
	s_or_b64 exec, exec, s[10:11]
	s_waitcnt lgkmcnt(0)
	v_add_u32_e32 v64, s49, v204
	ds_read_b128 v[66:69], v64
	ds_read_b128 v[76:79], v64 offset:32
	s_lshl_b32 s0, s66, 14
	s_add_i32 s0, s0, 0
	ds_read_b128 v[84:87], v64 offset:96
	s_waitcnt lgkmcnt(2)
	v_rcp_f32_e32 v73, v68
	v_rcp_f32_e32 v74, v69
	ds_read_b128 v[68:71], v64 offset:64
	v_rcp_f32_e32 v66, v66
	v_rcp_f32_e32 v72, v67
	s_waitcnt lgkmcnt(2)
	v_rcp_f32_e32 v75, v76
	v_rcp_f32_e32 v77, v77
	v_rcp_f32_e32 v78, v78
	v_rcp_f32_e32 v80, v79
	s_waitcnt lgkmcnt(0)
	v_rcp_f32_e32 v81, v68
	v_rcp_f32_e32 v83, v69
	v_rcp_f32_e32 v82, v70
	v_rcp_f32_e32 v79, v71
	v_rcp_f32_e32 v76, v84
	v_rcp_f32_e32 v71, v85
	v_rcp_f32_e32 v68, v86
	v_rcp_f32_e32 v69, v87
	v_lshlrev_b32_e32 v64, 11, v185
	v_lshlrev_b32_e32 v67, 2, v184
	s_cmp_lg_u32 s64, 1
	v_add3_u32 v70, s0, v64, v67
	s_barrier
; __device__ __forceinline__ int crow(int r, int hi) { return (r & 3) + 8 * (r >> 2) + 4 * hi; }
; template <int MODE, int ORD> ...
;     ...
;     __syncthreads();
;     float* X = (float*)lds + wq * 4096;
;     if (cst == 1) {
; #pragma unroll
;       for (int r = 0; r < 16; ++r) { const int orow = crow(r, hi);
; #pragma unroll
;         for (int d0 = 0; d0 < 4; ++d0) X[orow * 128 + d0 * 32 + r32] = o[d0][r] * rli[r]; }
;     }
	s_cbranch_scc1 .LBB0_203
	v_mul_f32_e32 v64, v0, v66
	v_mul_f32_e32 v65, v48, v66
	ds_write2_b32 v70, v64, v65 offset1:32
	v_mul_f32_e32 v64, v32, v66
	v_mul_f32_e32 v65, v16, v66
	ds_write2_b32 v70, v64, v65 offset0:64 offset1:96
	v_mul_f32_e32 v64, v1, v72
	v_mul_f32_e32 v65, v49, v72
	ds_write2_b32 v70, v64, v65 offset0:128 offset1:160
	v_mul_f32_e32 v64, v33, v72
	v_mul_f32_e32 v65, v17, v72
	ds_write2_b32 v70, v64, v65 offset0:192 offset1:224
	v_mul_f32_e32 v64, v2, v73
	v_mul_f32_e32 v65, v50, v73
	v_add_u32_e32 v84, 0x400, v70
	ds_write2_b32 v84, v64, v65 offset1:32
	v_mul_f32_e32 v64, v34, v73
	v_mul_f32_e32 v65, v18, v73
	ds_write2_b32 v84, v64, v65 offset0:64 offset1:96
	v_mul_f32_e32 v64, v3, v74
	v_mul_f32_e32 v65, v51, v74
	ds_write2_b32 v84, v64, v65 offset0:128 offset1:160
	v_mul_f32_e32 v64, v35, v74
	v_mul_f32_e32 v65, v19, v74
	ds_write2_b32 v84, v64, v65 offset0:192 offset1:224
	v_mul_f32_e32 v64, v4, v75
	v_mul_f32_e32 v65, v52, v75
	v_add_u32_e32 v84, 0x1000, v70
	ds_write2_b32 v84, v64, v65 offset1:32
	v_mul_f32_e32 v64, v36, v75
	v_mul_f32_e32 v65, v20, v75
	ds_write2_b32 v84, v64, v65 offset0:64 offset1:96
	v_mul_f32_e32 v64, v5, v77
	v_mul_f32_e32 v65, v53, v77
	ds_write2_b32 v84, v64, v65 offset0:128 offset1:160
	v_mul_f32_e32 v64, v37, v77
	v_mul_f32_e32 v65, v21, v77
	ds_write2_b32 v84, v64, v65 offset0:192 offset1:224
	v_mul_f32_e32 v64, v6, v78
	v_mul_f32_e32 v65, v54, v78
	v_add_u32_e32 v84, 0x1400, v70
	ds_write2_b32 v84, v64, v65 offset1:32
	v_mul_f32_e32 v64, v38, v78
	v_mul_f32_e32 v65, v22, v78
	ds_write2_b32 v84, v64, v65 offset0:64 offset1:96
	v_mul_f32_e32 v64, v7, v80
	v_mul_f32_e32 v65, v55, v80
	ds_write2_b32 v84, v64, v65 offset0:128 offset1:160
	v_mul_f32_e32 v64, v39, v80
	v_mul_f32_e32 v65, v23, v80
	ds_write2_b32 v84, v64, v65 offset0:192 offset1:224
	v_mul_f32_e32 v64, v8, v81
	v_mul_f32_e32 v65, v56, v81
	v_add_u32_e32 v84, 0x2000, v70
	ds_write2_b32 v84, v64, v65 offset1:32
	v_mul_f32_e32 v64, v40, v81
	v_mul_f32_e32 v65, v24, v81
	ds_write2_b32 v84, v64, v65 offset0:64 offset1:96
	v_mul_f32_e32 v64, v9, v83
	v_mul_f32_e32 v65, v57, v83
	ds_write2_b32 v84, v64, v65 offset0:128 offset1:160
	v_mul_f32_e32 v64, v41, v83
	v_mul_f32_e32 v65, v25, v83
	ds_write2_b32 v84, v64, v65 offset0:192 offset1:224
	v_mul_f32_e32 v64, v10, v82
	v_mul_f32_e32 v65, v58, v82
	v_add_u32_e32 v84, 0x2400, v70
	ds_write2_b32 v84, v64, v65 offset1:32
	v_mul_f32_e32 v64, v42, v82
	v_mul_f32_e32 v65, v26, v82
	ds_write2_b32 v84, v64, v65 offset0:64 offset1:96
	v_mul_f32_e32 v64, v11, v79
	v_mul_f32_e32 v65, v59, v79
	ds_write2_b32 v84, v64, v65 offset0:128 offset1:160
	v_mul_f32_e32 v64, v43, v79
	v_mul_f32_e32 v65, v27, v79
	ds_write2_b32 v84, v64, v65 offset0:192 offset1:224
	v_mul_f32_e32 v64, v12, v76
	v_mul_f32_e32 v65, v60, v76
	v_add_u32_e32 v84, 0x3000, v70
	ds_write2_b32 v84, v64, v65 offset1:32
	v_mul_f32_e32 v64, v44, v76
	v_mul_f32_e32 v65, v28, v76
	ds_write2_b32 v84, v64, v65 offset0:64 offset1:96
	v_mul_f32_e32 v64, v13, v71
	v_mul_f32_e32 v65, v61, v71
	ds_write2_b32 v84, v64, v65 offset0:128 offset1:160
	v_mul_f32_e32 v64, v45, v71
	v_mul_f32_e32 v65, v29, v71
	ds_write2_b32 v84, v64, v65 offset0:192 offset1:224
	v_mul_f32_e32 v64, v14, v68
	v_mul_f32_e32 v65, v62, v68
	v_add_u32_e32 v84, 0x3400, v70
	ds_write2_b32 v84, v64, v65 offset1:32
	v_mul_f32_e32 v64, v46, v68
	v_mul_f32_e32 v65, v30, v68
	ds_write2_b32 v84, v64, v65 offset0:64 offset1:96
	v_mul_f32_e32 v64, v15, v69
	v_mul_f32_e32 v65, v63, v69
	ds_write2_b32 v84, v64, v65 offset0:128 offset1:160
	v_mul_f32_e32 v64, v47, v69
	v_mul_f32_e32 v65, v31, v69
	ds_write2_b32 v84, v64, v65 offset0:192 offset1:224
